# dilated and neighbourhood attention PV: V-fragment LDS prefetch distance deepened from 2 to 3 MFMAs ahead (third fragment buffer)
# speedup vs baseline: 1.0030x; 1.0030x over previous
; #define LAS __attribute__((address_space(3)))
; #define MFMA32(a, b, c) __builtin_amdgcn_mfma_f32_32x32x16_bf16((a), (b), (c), 0, 0, 0)
; template <int KSTEPS, class Pol>
; __device__ __forceinline__ void attn_pass(LAS unsigned char* lds, const Pol& P, const bf16_t* qb, int ldq, const bf16_t* kb, int ldk, const bf16_t* vb, int ldv,
;                                           float qs, f32x16 (&O)[4], float& m, float& l) {
;     ...
;         LAS unsigned char* Kb = lds + st * A_STAGE + krow;
;         f32x16 S0, S1;
;         P.fill(S0, S1, qi, half, t, wave);
; #pragma unroll
;         for (int ks = 0; ks < KSTEPS; ++ks) {
;             const int so = ((2 * ks) ^ kx) << 4;
;             const bf16x8 a0 = *(const LAS bf16x8*)(Kb + so);
;             const bf16x8 a1 = *(const LAS bf16x8*)(Kb + 32 * KROWB + so);
;             S0 = MFMA32(a0, qf[ks], S0);
;             S1 = MFMA32(a1, qf[ks], S1);
;         }
;         S0 = S0 * qs; S1 = S1 * qs;
;         float mx = fmaxf(S0[0], S1[0]);
; #pragma unroll
;         for (int i = 1; i < 16; ++i) mx = fmaxf(fmaxf(mx, S0[i]), S1[i]);
;         mx = fmaxf(mx, __shfl_xor(mx, 32));
;         const float mnew = fmaxf(m, mx);
;         const float alpha = __builtin_amdgcn_exp2f(m - mnew);
;         m = mnew;
;     ...
;     auto pv_acc = [&](int st) __attribute__((always_inline)) {
;         LAS unsigned char* Vb = lds + st * A_STAGE;
; #pragma unroll
;         for (int s = 0; s < 4; ++s) {
; #pragma unroll
;             for (int blk = 0; blk < 4; ++blk) {
;                 const s16x4 lo = __builtin_amdgcn_ds_read_tr16_b64_v4i16((LAS s16x4*)(Vb + s * 4096 + voffs[blk][0]));
;                 const s16x4 hi = __builtin_amdgcn_ds_read_tr16_b64_v4i16((LAS s16x4*)(Vb + s * 4096 + voffs[blk][1]));
.LBB0_237:
	s_lshl_b32 s44, s74, 15
	s_add_i32 s44, s44, 0
	v_add_u32_e32 v0, s44, v160
	v_add_u32_e32 v6, v0, v161
	ds_read_b128 v[2:5], v6
	ds_read_b128 v[6:9], v6 offset:8192
	v_add_u32_e32 v200, v0, v162
	ds_read_b128 v[192:195], v200
	ds_read_b128 v[196:199], v200 offset:8192
	v_and_b32_e32 v15, 64, v234
	v_xor_b32_e32 v14, 32, v234
	v_add_u32_e32 v15, 64, v15
	s_waitcnt lgkmcnt(3)
	v_mfma_f32_32x32x16_bf16 v[96:111], v[2:5], v[112:115], v[96:111]
	v_cmp_lt_i32_e32 vcc, v14, v15
	s_nop 1
	v_cndmask_b32_e32 v14, v234, v14, vcc
	v_lshlrev_b32_e32 v14, 2, v14
	s_waitcnt lgkmcnt(2)
	v_mfma_f32_32x32x16_bf16 v[80:95], v[6:9], v[112:115], v[80:95]
	v_add_u32_e32 v6, v0, v163
	ds_read_b128 v[2:5], v6
	ds_read_b128 v[6:9], v6 offset:8192
	s_waitcnt lgkmcnt(3)
	v_mfma_f32_32x32x16_bf16 v[96:111], v[192:195], v[116:119], v[96:111]
	s_waitcnt lgkmcnt(2)
	v_mfma_f32_32x32x16_bf16 v[80:95], v[196:199], v[116:119], v[80:95]
	v_add_u32_e32 v200, v0, v164
	ds_read_b128 v[192:195], v200
	ds_read_b128 v[196:199], v200 offset:8192
	s_waitcnt lgkmcnt(3)
	v_mfma_f32_32x32x16_bf16 v[96:111], v[2:5], v[120:123], v[96:111]
	s_waitcnt lgkmcnt(2)
	v_mfma_f32_32x32x16_bf16 v[80:95], v[6:9], v[120:123], v[80:95]
	v_add_u32_e32 v6, v0, v165
	ds_read_b128 v[2:5], v6
	ds_read_b128 v[6:9], v6 offset:8192
	s_waitcnt lgkmcnt(3)
	v_mfma_f32_32x32x16_bf16 v[96:111], v[192:195], v[124:127], v[96:111]
	s_waitcnt lgkmcnt(2)
	v_mfma_f32_32x32x16_bf16 v[80:95], v[196:199], v[124:127], v[80:95]
	v_add_u32_e32 v200, v0, v166
	ds_read_b128 v[192:195], v200
	ds_read_b128 v[196:199], v200 offset:8192
	s_waitcnt lgkmcnt(3)
	v_mfma_f32_32x32x16_bf16 v[96:111], v[2:5], v[128:131], v[96:111]
	s_waitcnt lgkmcnt(2)
	v_mfma_f32_32x32x16_bf16 v[80:95], v[6:9], v[128:131], v[80:95]
	v_add_u32_e32 v6, v0, v167
	ds_read_b128 v[2:5], v6
	ds_read_b128 v[6:9], v6 offset:8192
	s_waitcnt lgkmcnt(3)
	v_mfma_f32_32x32x16_bf16 v[96:111], v[192:195], v[132:135], v[96:111]
	s_waitcnt lgkmcnt(2)
	v_mfma_f32_32x32x16_bf16 v[80:95], v[196:199], v[132:135], v[80:95]
	v_add_u32_e32 v200, v0, v168
	ds_read_b128 v[192:195], v200
	ds_read_b128 v[196:199], v200 offset:8192
	s_waitcnt lgkmcnt(3)
	v_mfma_f32_32x32x16_bf16 v[96:111], v[2:5], v[136:139], v[96:111]
	s_waitcnt lgkmcnt(2)
	v_mfma_f32_32x32x16_bf16 v[80:95], v[6:9], v[136:139], v[80:95]
	s_waitcnt lgkmcnt(1)
	v_mfma_f32_32x32x16_bf16 v[96:111], v[192:195], v[140:143], v[96:111]
	s_waitcnt lgkmcnt(0)
	v_mfma_f32_32x32x16_bf16 v[80:95], v[196:199], v[140:143], v[80:95]
	v_add_u32_e32 v201, s44, v169
	v_add_u32_e32 v202, s44, v170
	v_add_u32_e32 v203, s44, v171
	v_add_u32_e32 v204, s44, v172
	ds_read_b64_tr_b16 v[192:193], v201 offset:16384
	ds_read_b64_tr_b16 v[194:195], v202 offset:2048
	ds_read_b64_tr_b16 v[196:197], v203 offset:16384
	ds_read_b64_tr_b16 v[198:199], v204 offset:2048
	v_add_u32_e32 v2, s44, v173
	v_add_u32_e32 v3, s44, v174
	v_add_u32_e32 v4, s44, v175
	v_add_u32_e32 v5, s44, v176
	ds_read_b64_tr_b16 v[226:227], v2 offset:16384
	ds_read_b64_tr_b16 v[228:229], v3 offset:2048
	v_max_f32_e32 v15, v96, v80
	v_max3_f32 v15, v15, v97, v81
	v_max3_f32 v15, v15, v98, v82
	v_max3_f32 v15, v15, v99, v83
	v_max3_f32 v15, v15, v100, v84
	v_max3_f32 v15, v15, v101, v85
	v_max3_f32 v15, v15, v102, v86
	v_max3_f32 v15, v15, v103, v87
	v_max3_f32 v15, v15, v104, v88
	v_max3_f32 v15, v15, v105, v89
	v_max3_f32 v15, v15, v106, v90
	v_max3_f32 v15, v15, v107, v91
	v_max3_f32 v15, v15, v108, v92
	v_max3_f32 v15, v15, v109, v93
	v_max3_f32 v15, v15, v110, v94
	v_max3_f32 v15, v15, v111, v95
	v_mul_f32_e64 v15, v15, s20
	ds_bpermute_b32 v14, v14, v15
	s_waitcnt lgkmcnt(0)
	v_max3_f32 v14, v181, v15, v14
	v_sub_f32_e32 v0, v181, v14
	v_exp_f32_e32 v0, v0
	s_nop 0
	v_cmp_neq_f32_e32 vcc, 1.0, v0
	s_cbranch_vccz .LBB0_239
	v_pk_mul_f32 v[78:79], v[78:79], v[0:1] op_sel_hi:[1,0]
	v_pk_mul_f32 v[76:77], v[76:77], v[0:1] op_sel_hi:[1,0]
	v_pk_mul_f32 v[74:75], v[74:75], v[0:1] op_sel_hi:[1,0]
	v_pk_mul_f32 v[72:73], v[72:73], v[0:1] op_sel_hi:[1,0]
	v_pk_mul_f32 v[70:71], v[70:71], v[0:1] op_sel_hi:[1,0]
	v_pk_mul_f32 v[68:69], v[68:69], v[0:1] op_sel_hi:[1,0]
	v_pk_mul_f32 v[66:67], v[66:67], v[0:1] op_sel_hi:[1,0]
	v_pk_mul_f32 v[64:65], v[64:65], v[0:1] op_sel_hi:[1,0]
	v_pk_mul_f32 v[62:63], v[62:63], v[0:1] op_sel_hi:[1,0]
	v_pk_mul_f32 v[60:61], v[60:61], v[0:1] op_sel_hi:[1,0]
	v_pk_mul_f32 v[58:59], v[58:59], v[0:1] op_sel_hi:[1,0]
	v_pk_mul_f32 v[56:57], v[56:57], v[0:1] op_sel_hi:[1,0]
	v_pk_mul_f32 v[54:55], v[54:55], v[0:1] op_sel_hi:[1,0]
	v_pk_mul_f32 v[52:53], v[52:53], v[0:1] op_sel_hi:[1,0]
	v_pk_mul_f32 v[50:51], v[50:51], v[0:1] op_sel_hi:[1,0]
	v_pk_mul_f32 v[48:49], v[48:49], v[0:1] op_sel_hi:[1,0]
	v_pk_mul_f32 v[46:47], v[46:47], v[0:1] op_sel_hi:[1,0]
	v_pk_mul_f32 v[44:45], v[44:45], v[0:1] op_sel_hi:[1,0]
	v_pk_mul_f32 v[42:43], v[42:43], v[0:1] op_sel_hi:[1,0]
	v_pk_mul_f32 v[40:41], v[40:41], v[0:1] op_sel_hi:[1,0]
	v_pk_mul_f32 v[38:39], v[38:39], v[0:1] op_sel_hi:[1,0]
	v_pk_mul_f32 v[36:37], v[36:37], v[0:1] op_sel_hi:[1,0]
	v_pk_mul_f32 v[34:35], v[34:35], v[0:1] op_sel_hi:[1,0]
	v_pk_mul_f32 v[32:33], v[32:33], v[0:1] op_sel_hi:[1,0]
	v_pk_mul_f32 v[30:31], v[30:31], v[0:1] op_sel_hi:[1,0]
	v_pk_mul_f32 v[28:29], v[28:29], v[0:1] op_sel_hi:[1,0]
	v_pk_mul_f32 v[26:27], v[26:27], v[0:1] op_sel_hi:[1,0]
	v_pk_mul_f32 v[24:25], v[24:25], v[0:1] op_sel_hi:[1,0]
	v_pk_mul_f32 v[22:23], v[22:23], v[0:1] op_sel_hi:[1,0]
	v_pk_mul_f32 v[20:21], v[20:21], v[0:1] op_sel_hi:[1,0]
	v_pk_mul_f32 v[18:19], v[18:19], v[0:1] op_sel_hi:[1,0]
	v_pk_mul_f32 v[16:17], v[16:17], v[0:1] op_sel_hi:[1,0]
; #define LAS __attribute__((address_space(3)))
; __device__ __forceinline__ unsigned pk2(float lo, float hi) { f32x2 v = {lo, hi}; bf16x2_t b = __builtin_convertvector(v, bf16x2_t); return __builtin_bit_cast(unsigned, b); }
; #define MFMA32(a, b, c) __builtin_amdgcn_mfma_f32_32x32x16_bf16((a), (b), (c), 0, 0, 0)
; template <int KSTEPS, class Pol>
; __device__ __forceinline__ void attn_pass(LAS unsigned char* lds, const Pol& P, const bf16_t* qb, int ldq, const bf16_t* kb, int ldk, const bf16_t* vb, int ldv,
;                                           float qs, f32x16 (&O)[4], float& m, float& l) {
;     ...
;             const f32x2 nm = {-mnew, -mnew};
; #pragma unroll
;             for (int i = 0; i < 16; i += 2) { const f32x2 a = (f32x2){S0[i], S0[i + 1]} + nm, b = (f32x2){S1[i], S1[i + 1]} + nm; S0[i] = a.x; S0[i + 1] = a.y; S1[i] = b.x; S1[i + 1] = b.y; }
;         }
;         f32x2 ls2 = {0.f, 0.f};
; #pragma unroll
;         for (int s = 0; s < 4; ++s) {
;             unsigned w[4];
; #pragma unroll
;             for (int e = 0; e < 4; ++e) {
;                 const int i = 8 * (s & 1) + 2 * e;
;                 f32x2 pv;
;                 pv.x = __builtin_amdgcn_exp2f(s < 2 ? S0[i] : S1[i]); pv.y = __builtin_amdgcn_exp2f(s < 2 ? S0[i + 1] : S1[i + 1]);
;                 ls2 = ls2 + pv;
;                 w[e] = pk2(pv.x, pv.y);
;             }
;             u32x4 wv; wv.x = w[0]; wv.y = w[1]; wv.z = w[2]; wv.w = w[3];
;             pf[s] = __builtin_bit_cast(bf16x8, wv);
;         }
;         l = l * alpha + (ls2.x + ls2.y);
;     ...
;     auto pv_acc = [&](int st) __attribute__((always_inline)) {
;         LAS unsigned char* Vb = lds + st * A_STAGE;
; #pragma unroll
;         for (int s = 0; s < 4; ++s) {
; #pragma unroll
;             for (int blk = 0; blk < 4; ++blk) {
;                 const s16x4 lo = __builtin_amdgcn_ds_read_tr16_b64_v4i16((LAS s16x4*)(Vb + s * 4096 + voffs[blk][0]));
;                 const s16x4 hi = __builtin_amdgcn_ds_read_tr16_b64_v4i16((LAS s16x4*)(Vb + s * 4096 + voffs[blk][1]));
;                 const bf16x8 va = __builtin_shufflevector(lo, hi, 0, 1, 2, 3, 4, 5, 6, 7);
;                 O[blk] = MFMA32(va, pf[s], O[blk]);
;             }
;         }
.LBB0_239:
	v_pk_fma_f32 v[96:97], v[96:97], s[20:21], v[14:15] op_sel_hi:[1,0,0] neg_lo:[0,0,1] neg_hi:[0,0,1]
	v_pk_fma_f32 v[98:99], v[98:99], s[20:21], v[14:15] op_sel_hi:[1,0,0] neg_lo:[0,0,1] neg_hi:[0,0,1]
	v_pk_fma_f32 v[100:101], v[100:101], s[20:21], v[14:15] op_sel_hi:[1,0,0] neg_lo:[0,0,1] neg_hi:[0,0,1]
	v_pk_fma_f32 v[102:103], v[102:103], s[20:21], v[14:15] op_sel_hi:[1,0,0] neg_lo:[0,0,1] neg_hi:[0,0,1]
	v_exp_f32_e32 v96, v96
	v_exp_f32_e32 v97, v97
	v_exp_f32_e32 v98, v98
	v_exp_f32_e32 v99, v99
	v_exp_f32_e32 v100, v100
	v_exp_f32_e32 v101, v101
	v_exp_f32_e32 v102, v102
	v_exp_f32_e32 v103, v103
	v_pk_fma_f32 v[104:105], v[104:105], s[20:21], v[14:15] op_sel_hi:[1,0,0] neg_lo:[0,0,1] neg_hi:[0,0,1]
	v_pk_fma_f32 v[106:107], v[106:107], s[20:21], v[14:15] op_sel_hi:[1,0,0] neg_lo:[0,0,1] neg_hi:[0,0,1]
	v_cvt_pk_bf16_f32 v6, v96, v97
	v_cvt_pk_bf16_f32 v7, v98, v99
	v_cvt_pk_bf16_f32 v8, v100, v101
	v_cvt_pk_bf16_f32 v9, v102, v103
	v_pk_fma_f32 v[108:109], v[108:109], s[20:21], v[14:15] op_sel_hi:[1,0,0] neg_lo:[0,0,1] neg_hi:[0,0,1]
	v_pk_fma_f32 v[110:111], v[110:111], s[20:21], v[14:15] op_sel_hi:[1,0,0] neg_lo:[0,0,1] neg_hi:[0,0,1]
	v_pk_add_f32 v[224:225], v[96:97], v[98:99]
	s_waitcnt lgkmcnt(4)
	v_mfma_f32_32x32x16_bf16 v[64:79], v[192:195], v[6:9], v[64:79]
	ds_read_b64_tr_b16 v[192:193], v4 offset:16384
	ds_read_b64_tr_b16 v[194:195], v5 offset:2048
	v_exp_f32_e32 v104, v104
	v_exp_f32_e32 v105, v105
	v_exp_f32_e32 v106, v106
	v_exp_f32_e32 v107, v107
	v_pk_add_f32 v[224:225], v[100:101], v[224:225]
	s_waitcnt lgkmcnt(4)
	v_mfma_f32_32x32x16_bf16 v[48:63], v[196:199], v[6:9], v[48:63]
	ds_read_b64_tr_b16 v[196:197], v201 offset:20480
	ds_read_b64_tr_b16 v[198:199], v202 offset:6144
	v_exp_f32_e32 v108, v108
	v_exp_f32_e32 v109, v109
	v_exp_f32_e32 v110, v110
	v_exp_f32_e32 v111, v111
	v_pk_add_f32 v[224:225], v[102:103], v[224:225]
	s_waitcnt lgkmcnt(4)
	v_mfma_f32_32x32x16_bf16 v[32:47], v[226:229], v[6:9], v[32:47]
	ds_read_b64_tr_b16 v[226:227], v203 offset:20480
	ds_read_b64_tr_b16 v[228:229], v204 offset:6144
	v_cvt_pk_bf16_f32 v10, v104, v105
	v_cvt_pk_bf16_f32 v11, v106, v107
	v_cvt_pk_bf16_f32 v12, v108, v109
	v_cvt_pk_bf16_f32 v13, v110, v111
	v_pk_add_f32 v[224:225], v[104:105], v[224:225]
	s_waitcnt lgkmcnt(4)
	v_mfma_f32_32x32x16_bf16 v[16:31], v[192:195], v[6:9], v[16:31]
	ds_read_b64_tr_b16 v[192:193], v2 offset:20480
	ds_read_b64_tr_b16 v[194:195], v3 offset:6144
	v_pk_add_f32 v[224:225], v[106:107], v[224:225]
	v_pk_fma_f32 v[80:81], v[80:81], s[20:21], v[14:15] op_sel_hi:[1,0,0] neg_lo:[0,0,1] neg_hi:[0,0,1]
	v_pk_fma_f32 v[82:83], v[82:83], s[20:21], v[14:15] op_sel_hi:[1,0,0] neg_lo:[0,0,1] neg_hi:[0,0,1]
	v_pk_fma_f32 v[84:85], v[84:85], s[20:21], v[14:15] op_sel_hi:[1,0,0] neg_lo:[0,0,1] neg_hi:[0,0,1]
	v_pk_fma_f32 v[86:87], v[86:87], s[20:21], v[14:15] op_sel_hi:[1,0,0] neg_lo:[0,0,1] neg_hi:[0,0,1]
	s_waitcnt lgkmcnt(4)
	v_mfma_f32_32x32x16_bf16 v[64:79], v[196:199], v[10:13], v[64:79]
	ds_read_b64_tr_b16 v[196:197], v4 offset:20480
	ds_read_b64_tr_b16 v[198:199], v5 offset:6144
	v_exp_f32_e32 v80, v80
	v_exp_f32_e32 v81, v81
	v_exp_f32_e32 v82, v82
	v_exp_f32_e32 v83, v83
	v_pk_add_f32 v[224:225], v[108:109], v[224:225]
	s_waitcnt lgkmcnt(4)
	v_mfma_f32_32x32x16_bf16 v[48:63], v[226:229], v[10:13], v[48:63]
	ds_read_b64_tr_b16 v[226:227], v201 offset:24576
	ds_read_b64_tr_b16 v[228:229], v202 offset:10240
	v_exp_f32_e32 v84, v84
	v_exp_f32_e32 v85, v85
	v_exp_f32_e32 v86, v86
	v_exp_f32_e32 v87, v87
	v_pk_add_f32 v[224:225], v[110:111], v[224:225]
	s_waitcnt lgkmcnt(4)
	v_mfma_f32_32x32x16_bf16 v[32:47], v[192:195], v[10:13], v[32:47]
	ds_read_b64_tr_b16 v[192:193], v203 offset:24576
	ds_read_b64_tr_b16 v[194:195], v204 offset:10240
	v_cvt_pk_bf16_f32 v6, v80, v81
	v_cvt_pk_bf16_f32 v7, v82, v83
	v_cvt_pk_bf16_f32 v8, v84, v85
	v_cvt_pk_bf16_f32 v9, v86, v87
	v_pk_add_f32 v[224:225], v[80:81], v[224:225]
	s_waitcnt lgkmcnt(4)
	v_mfma_f32_32x32x16_bf16 v[16:31], v[196:199], v[10:13], v[16:31]
	ds_read_b64_tr_b16 v[196:197], v2 offset:24576
	ds_read_b64_tr_b16 v[198:199], v3 offset:10240
	v_pk_add_f32 v[224:225], v[82:83], v[224:225]
	v_pk_fma_f32 v[88:89], v[88:89], s[20:21], v[14:15] op_sel_hi:[1,0,0] neg_lo:[0,0,1] neg_hi:[0,0,1]
	v_pk_fma_f32 v[90:91], v[90:91], s[20:21], v[14:15] op_sel_hi:[1,0,0] neg_lo:[0,0,1] neg_hi:[0,0,1]
	v_pk_fma_f32 v[92:93], v[92:93], s[20:21], v[14:15] op_sel_hi:[1,0,0] neg_lo:[0,0,1] neg_hi:[0,0,1]
	v_pk_fma_f32 v[94:95], v[94:95], s[20:21], v[14:15] op_sel_hi:[1,0,0] neg_lo:[0,0,1] neg_hi:[0,0,1]
	s_waitcnt lgkmcnt(4)
	v_mfma_f32_32x32x16_bf16 v[64:79], v[226:229], v[6:9], v[64:79]
	ds_read_b64_tr_b16 v[226:227], v4 offset:24576
	ds_read_b64_tr_b16 v[228:229], v5 offset:10240
	v_exp_f32_e32 v88, v88
	v_exp_f32_e32 v89, v89
	v_exp_f32_e32 v90, v90
	v_exp_f32_e32 v91, v91
	v_pk_add_f32 v[224:225], v[84:85], v[224:225]
	s_waitcnt lgkmcnt(4)
	v_mfma_f32_32x32x16_bf16 v[48:63], v[192:195], v[6:9], v[48:63]
	ds_read_b64_tr_b16 v[192:193], v201 offset:28672
	ds_read_b64_tr_b16 v[194:195], v202 offset:14336
	v_exp_f32_e32 v92, v92
	v_exp_f32_e32 v93, v93
	v_exp_f32_e32 v94, v94
	v_exp_f32_e32 v95, v95
	v_pk_add_f32 v[224:225], v[86:87], v[224:225]
	s_waitcnt lgkmcnt(4)
	v_mfma_f32_32x32x16_bf16 v[32:47], v[196:199], v[6:9], v[32:47]
	ds_read_b64_tr_b16 v[196:197], v203 offset:28672
	ds_read_b64_tr_b16 v[198:199], v204 offset:14336
	v_cvt_pk_bf16_f32 v10, v88, v89
	v_cvt_pk_bf16_f32 v11, v90, v91
	v_cvt_pk_bf16_f32 v12, v92, v93
	v_cvt_pk_bf16_f32 v13, v94, v95
	v_pk_add_f32 v[224:225], v[88:89], v[224:225]
	s_waitcnt lgkmcnt(4)
	v_mfma_f32_32x32x16_bf16 v[16:31], v[226:229], v[6:9], v[16:31]
	ds_read_b64_tr_b16 v[226:227], v2 offset:28672
	ds_read_b64_tr_b16 v[228:229], v3 offset:14336
	v_pk_add_f32 v[224:225], v[90:91], v[224:225]
	s_waitcnt lgkmcnt(4)
	v_mfma_f32_32x32x16_bf16 v[64:79], v[192:195], v[10:13], v[64:79]
	ds_read_b64_tr_b16 v[192:193], v4 offset:28672
	ds_read_b64_tr_b16 v[194:195], v5 offset:14336
	v_pk_add_f32 v[224:225], v[92:93], v[224:225]
	s_waitcnt lgkmcnt(4)
	v_mfma_f32_32x32x16_bf16 v[48:63], v[196:199], v[10:13], v[48:63]
	v_pk_add_f32 v[224:225], v[94:95], v[224:225]
	s_waitcnt lgkmcnt(2)
	v_mfma_f32_32x32x16_bf16 v[32:47], v[226:229], v[10:13], v[32:47]
	v_add_f32_e32 v15, v224, v225
	s_waitcnt lgkmcnt(0)
	v_mfma_f32_32x32x16_bf16 v[16:31], v[192:195], v[10:13], v[16:31]
	v_fmac_f32_e32 v15, v180, v0
	s_nop 0
	v_mov_b32_e32 v180, v15
	s_cmp_gt_u32 s71, 4
	s_cbranch_scc0 .LBB0_241
	s_branch .LBB0_246

;     __device__ __forceinline__ float bias(int qi, int half, int t, int jc) const {
;         const int j = jc + 4 * half;
;         const int r = R + (qi >> 6), c = qi & 63, kr = kr_lo + t, c0 = min(max(c - 8, 0), 48);
;         const bool ok = (j >= c0) && (j < c0 + 16);
;         const int idx = min(max((kr - r + 7) * 31 + (j - c + 15), 0), 15 * 31 - 1);
;         const float bv = rpb[idx];
;         return ok ? bv : -__builtin_inff();
;     }
;     __device__ __forceinline__ void fill(f32x16& S0, f32x16& S1, int qi, int half, int t, int) const {
; #pragma unroll
;         for (int i = 0; i < 16; ++i) { const int jc = 8 * (i >> 2) + (i & 3); S0[i] = bias(qi, half, t, jc); S1[i] = bias(qi, half, t, 32 + jc); }
.LBB0_463:
	s_add_i32 s51, s42, s49
	s_cmp_lt_u32 s51, s46
	s_cselect_b64 vcc, -1, 0
	s_cmp_gt_u32 s51, s47
	s_cselect_b64 s[52:53], -1, 0
	s_or_b64 s[52:53], vcc, s[52:53]
	s_and_b64 vcc, exec, s[52:53]
	s_cbranch_vccnz .LBB0_467
	v_subrev_u32_e32 v2, 59, v172
	v_subrev_u32_e32 v3, 27, v172
	v_subrev_u32_e32 v4, 58, v172
	v_subrev_u32_e32 v5, 26, v172
	v_subrev_u32_e32 v6, 57, v172
	v_subrev_u32_e32 v7, 25, v172
	v_subrev_u32_e32 v8, 56, v172
	v_subrev_u32_e32 v9, 24, v172
	v_med3_i32 v2, v2, 0, v239
	s_add_i32 vcc_lo, 0, 0x18000
	v_med3_i32 v3, v3, 0, v239
	v_med3_i32 v4, v4, 0, v239
	v_med3_i32 v5, v5, 0, v239
	v_med3_i32 v6, v6, 0, v239
	v_med3_i32 v7, v7, 0, v239
	v_med3_i32 v8, v8, 0, v239
	v_med3_i32 v9, v9, 0, v239
	v_readlane_b32 s52, v250, 1
	v_lshl_add_u32 v2, v2, 2, vcc_lo
	v_lshl_add_u32 v3, v3, 2, vcc_lo
	v_lshl_add_u32 v4, v4, 2, vcc_lo
	v_lshl_add_u32 v5, v5, 2, vcc_lo
	v_lshl_add_u32 v6, v6, 2, vcc_lo
	v_lshl_add_u32 v7, v7, 2, vcc_lo
	v_lshl_add_u32 v8, v8, 2, vcc_lo
	v_lshl_add_u32 v9, v9, 2, vcc_lo
	v_readlane_b32 s53, v250, 2
	ds_read_b32 v2, v2
	ds_read_b32 v3, v3
	ds_read_b32 v4, v4
	ds_read_b32 v5, v5
	ds_read_b32 v6, v6
	ds_read_b32 v7, v7
	ds_read_b32 v8, v8
	ds_read_b32 v9, v9
	s_waitcnt lgkmcnt(6)
	v_cndmask_b32_e64 v80, v238, v3, s[52:53]
	v_readlane_b32 s52, v250, 3
	v_readlane_b32 s53, v250, 4
	v_cndmask_b32_e64 v96, v2, v238, s[36:37]
	v_subrev_u32_e32 v2, 51, v172
	s_waitcnt lgkmcnt(5)
	v_cndmask_b32_e64 v97, v4, v238, s[52:53]
	v_readlane_b32 s52, v250, 5
	v_readlane_b32 s53, v250, 6
	v_subrev_u32_e32 v3, 19, v172
	v_subrev_u32_e32 v4, 50, v172
	s_waitcnt lgkmcnt(4)
	v_cndmask_b32_e64 v81, v238, v5, s[52:53]
	v_readlane_b32 s52, v250, 7
	v_readlane_b32 s53, v250, 8
	v_subrev_u32_e32 v5, 18, v172
	v_med3_i32 v2, v2, 0, v239
	s_waitcnt lgkmcnt(3)
	v_cndmask_b32_e64 v98, v6, v238, s[52:53]
	v_readlane_b32 s52, v250, 9
	v_readlane_b32 s53, v250, 10
	v_subrev_u32_e32 v6, 49, v172
	v_med3_i32 v3, v3, 0, v239
	s_waitcnt lgkmcnt(2)
	v_cndmask_b32_e64 v82, v238, v7, s[52:53]
	v_readlane_b32 s52, v250, 11
	v_readlane_b32 s53, v250, 12
	v_subrev_u32_e32 v7, 17, v172
	v_med3_i32 v4, v4, 0, v239
	s_waitcnt lgkmcnt(1)
	v_cndmask_b32_e64 v99, v8, v238, s[52:53]
	v_readlane_b32 s52, v250, 13
	v_readlane_b32 s53, v250, 14
	v_subrev_u32_e32 v8, 48, v172
	v_med3_i32 v5, v5, 0, v239
	s_waitcnt lgkmcnt(0)
	v_cndmask_b32_e64 v83, v238, v9, s[52:53]
	v_add_u32_e32 v9, -16, v172
	v_med3_i32 v6, v6, 0, v239
	v_med3_i32 v7, v7, 0, v239
	v_med3_i32 v8, v8, 0, v239
	v_med3_i32 v9, v9, 0, v239
	v_lshl_add_u32 v2, v2, 2, vcc_lo
	v_lshl_add_u32 v3, v3, 2, vcc_lo
	v_lshl_add_u32 v4, v4, 2, vcc_lo
	v_lshl_add_u32 v5, v5, 2, vcc_lo
	v_lshl_add_u32 v6, v6, 2, vcc_lo
	v_lshl_add_u32 v7, v7, 2, vcc_lo
	v_lshl_add_u32 v8, v8, 2, vcc_lo
	v_lshl_add_u32 v9, v9, 2, vcc_lo
	ds_read_b32 v2, v2
	ds_read_b32 v3, v3
	ds_read_b32 v4, v4
	ds_read_b32 v5, v5
	ds_read_b32 v6, v6
	ds_read_b32 v7, v7
	ds_read_b32 v8, v8
	ds_read_b32 v9, v9
	v_readlane_b32 s52, v250, 15
	v_readlane_b32 s53, v250, 16
	s_waitcnt lgkmcnt(6)
	v_cndmask_b32_e64 v84, v238, v3, s[54:55]
	s_waitcnt lgkmcnt(5)
	v_cndmask_b32_e64 v101, v4, v238, s[56:57]
	v_cndmask_b32_e64 v100, v2, v238, s[52:53]
	s_waitcnt lgkmcnt(4)
	v_cndmask_b32_e64 v85, v238, v5, s[58:59]
	s_waitcnt lgkmcnt(3)
	v_cndmask_b32_e64 v102, v6, v238, s[60:61]
	v_subrev_u32_e32 v2, 43, v172
	v_add_u32_e32 v3, -11, v172
	v_subrev_u32_e32 v4, 42, v172
	v_add_u32_e32 v5, -10, v172
	v_subrev_u32_e32 v6, 41, v172
	s_waitcnt lgkmcnt(2)
	v_cndmask_b32_e64 v86, v238, v7, s[62:63]
	s_waitcnt lgkmcnt(1)
	v_cndmask_b32_e64 v103, v8, v238, s[64:65]
	s_waitcnt lgkmcnt(0)
	v_cndmask_b32_e64 v87, v238, v9, s[40:41]
	v_med3_i32 v2, v2, 0, v239
	v_med3_i32 v3, v3, 0, v239
	v_med3_i32 v4, v4, 0, v239
	v_med3_i32 v5, v5, 0, v239
	v_med3_i32 v6, v6, 0, v239
	v_add_u32_e32 v7, -9, v172
	v_subrev_u32_e32 v8, 40, v172
	v_add_u32_e32 v9, -8, v172
	v_lshl_add_u32 v2, v2, 2, vcc_lo
	v_lshl_add_u32 v3, v3, 2, vcc_lo
	v_lshl_add_u32 v4, v4, 2, vcc_lo
	v_lshl_add_u32 v5, v5, 2, vcc_lo
	v_lshl_add_u32 v6, v6, 2, vcc_lo
	v_med3_i32 v7, v7, 0, v239
	v_med3_i32 v8, v8, 0, v239
	v_med3_i32 v9, v9, 0, v239
	v_lshl_add_u32 v7, v7, 2, vcc_lo
	v_lshl_add_u32 v8, v8, 2, vcc_lo
	v_lshl_add_u32 v9, v9, 2, vcc_lo
	ds_read_b32 v2, v2
	ds_read_b32 v3, v3
	ds_read_b32 v4, v4
	ds_read_b32 v10, v5
	ds_read_b32 v5, v6
	ds_read_b32 v11, v7
	ds_read_b32 v6, v8
	ds_read_b32 v12, v9
	s_waitcnt lgkmcnt(7)
	v_cndmask_b32_e64 v104, v238, v2, s[68:69]
	v_subrev_u32_e32 v2, 35, v172
	v_med3_i32 v2, v2, 0, v239
	s_waitcnt lgkmcnt(1)
	v_cndmask_b32_e64 v107, v238, v6, s[80:81]
	v_lshl_add_u32 v6, v2, 2, vcc_lo
	v_add_u32_e32 v2, -3, v172
	v_med3_i32 v2, v2, 0, v239
	v_lshl_add_u32 v7, v2, 2, vcc_lo
	v_subrev_u32_e32 v2, 34, v172
	v_med3_i32 v2, v2, 0, v239
	v_lshl_add_u32 v8, v2, 2, vcc_lo
	v_add_u32_e32 v2, -2, v172
	v_med3_i32 v2, v2, 0, v239
	v_lshl_add_u32 v9, v2, 2, vcc_lo
	v_subrev_u32_e32 v2, 33, v172
	v_med3_i32 v2, v2, 0, v239
	v_lshl_add_u32 v13, v2, 2, vcc_lo
	v_add_u32_e32 v2, -1, v172
	s_lshl_b32 s51, s50, 15
	v_med3_i32 v2, v2, 0, v239
	s_add_i32 s51, s51, 0
	v_lshl_add_u32 v14, v2, 2, vcc_lo
	v_subrev_u32_e32 v2, 32, v172
	v_add_u32_e32 v0, s51, v145
	v_med3_i32 v2, v2, 0, v239
	v_lshl_add_u32 v15, v2, 2, vcc_lo
	v_med3_i32 v2, v172, 0, v239
	v_add_u32_e32 v90, v0, v156
	v_cndmask_b32_e64 v88, v238, v3, s[70:71]
	v_cndmask_b32_e64 v105, v238, v4, s[72:73]
	v_cndmask_b32_e64 v106, v238, v5, s[76:77]
	v_lshl_add_u32 v89, v2, 2, vcc_lo
	ds_read_b128 v[2:5], v90
	ds_read_b32 v6, v6
	ds_read_b32 v92, v7
	ds_read_b32 v7, v8
	ds_read_b32 v93, v9
	ds_read_b32 v8, v13
	ds_read_b32 v13, v14
	ds_read_b32 v9, v15
	ds_read_b32 v14, v89
	s_waitcnt lgkmcnt(7)
; #define LAS __attribute__((address_space(3)))
; #define MFMA32(a, b, c) __builtin_amdgcn_mfma_f32_32x32x16_bf16((a), (b), (c), 0, 0, 0)
; template <int KSTEPS, class Pol>
; __device__ __forceinline__ void attn_pass(LAS unsigned char* lds, const Pol& P, const bf16_t* qb, int ldq, const bf16_t* kb, int ldk, const bf16_t* vb, int ldv,
;                                           float qs, f32x16 (&O)[4], float& m, float& l) {
;     ...
;         LAS unsigned char* Kb = lds + st * A_STAGE + krow;
;         f32x16 S0, S1;
;         P.fill(S0, S1, qi, half, t, wave);
; #pragma unroll
;         for (int ks = 0; ks < KSTEPS; ++ks) {
;             const int so = ((2 * ks) ^ kx) << 4;
;             const bf16x8 a0 = *(const LAS bf16x8*)(Kb + so);
;             const bf16x8 a1 = *(const LAS bf16x8*)(Kb + 32 * KROWB + so);
;             S0 = MFMA32(a0, qf[ks], S0);
;             S1 = MFMA32(a1, qf[ks], S1);
;         }
;         S0 = S0 * qs; S1 = S1 * qs;
;         float mx = fmaxf(S0[0], S1[0]);
; #pragma unroll
;         for (int i = 1; i < 16; ++i) mx = fmaxf(fmaxf(mx, S0[i]), S1[i]);
;         mx = fmaxf(mx, __shfl_xor(mx, 32));
;         const float mnew = fmaxf(m, mx);
;         const float alpha = __builtin_amdgcn_exp2f(m - mnew);
;         m = mnew;
;     ...
;     auto pv_acc = [&](int st) __attribute__((always_inline)) {
;         LAS unsigned char* Vb = lds + st * A_STAGE;
; #pragma unroll
;         for (int s = 0; s < 4; ++s) {
; #pragma unroll
;             for (int blk = 0; blk < 4; ++blk) {
;                 const s16x4 lo = __builtin_amdgcn_ds_read_tr16_b64_v4i16((LAS s16x4*)(Vb + s * 4096 + voffs[blk][0]));
;                 const s16x4 hi = __builtin_amdgcn_ds_read_tr16_b64_v4i16((LAS s16x4*)(Vb + s * 4096 + voffs[blk][1]));
	v_cndmask_b32_e64 v108, v238, v6, s[84:85]
	s_waitcnt lgkmcnt(5)
	v_cndmask_b32_e64 v109, v238, v7, s[88:89]
	s_waitcnt lgkmcnt(3)
	v_cndmask_b32_e64 v110, v238, v8, s[92:93]
	s_waitcnt lgkmcnt(1)
	v_cndmask_b32_e64 v111, v238, v9, s[96:97]
	ds_read_b128 v[6:9], v90 offset:8192
	v_cndmask_b32_e64 v89, v238, v10, s[74:75]
	v_cndmask_b32_e64 v90, v238, v11, s[78:79]
	v_cndmask_b32_e64 v91, v238, v12, s[82:83]
	v_cndmask_b32_e64 v92, v238, v92, s[86:87]
	v_cndmask_b32_e64 v93, v238, v93, s[90:91]
	v_cndmask_b32_e64 v94, v238, v13, s[94:95]
	s_waitcnt lgkmcnt(1)
	v_cndmask_b32_e64 v95, v238, v14, s[2:3]
	v_mfma_f32_32x32x16_bf16 v[96:111], v[2:5], v[112:115], v[96:111]
	v_and_b32_e32 v15, 64, v234
	v_xor_b32_e32 v14, 32, v234
	v_add_u32_e32 v15, 64, v15
	v_cmp_lt_i32_e32 vcc, v14, v15
	s_nop 1
	v_cndmask_b32_e32 v14, v234, v14, vcc
	s_waitcnt lgkmcnt(0)
	v_mfma_f32_32x32x16_bf16 v[80:95], v[6:9], v[112:115], v[80:95]
	v_add_u32_e32 v6, v0, v157
	ds_read_b128 v[2:5], v6
	ds_read_b128 v[6:9], v6 offset:8192
	v_add_u32_e32 v200, v0, v158
	ds_read_b128 v[192:195], v200
	ds_read_b128 v[196:199], v200 offset:8192
	v_lshlrev_b32_e32 v14, 2, v14
	s_waitcnt lgkmcnt(3)
	v_mfma_f32_32x32x16_bf16 v[96:111], v[2:5], v[116:119], v[96:111]
	s_waitcnt lgkmcnt(2)
	v_mfma_f32_32x32x16_bf16 v[80:95], v[6:9], v[116:119], v[80:95]
	v_add_u32_e32 v6, v0, v159
	ds_read_b128 v[2:5], v6
	ds_read_b128 v[6:9], v6 offset:8192
	s_waitcnt lgkmcnt(3)
	v_mfma_f32_32x32x16_bf16 v[96:111], v[192:195], v[120:123], v[96:111]
	s_waitcnt lgkmcnt(2)
	v_mfma_f32_32x32x16_bf16 v[80:95], v[196:199], v[120:123], v[80:95]
	v_add_u32_e32 v200, v0, v160
	ds_read_b128 v[192:195], v200
	ds_read_b128 v[196:199], v200 offset:8192
	s_waitcnt lgkmcnt(3)
	v_mfma_f32_32x32x16_bf16 v[96:111], v[2:5], v[124:127], v[96:111]
	s_waitcnt lgkmcnt(2)
	v_mfma_f32_32x32x16_bf16 v[80:95], v[6:9], v[124:127], v[80:95]
	v_add_u32_e32 v6, v0, v161
	ds_read_b128 v[2:5], v6
	ds_read_b128 v[6:9], v6 offset:8192
	s_waitcnt lgkmcnt(3)
	v_mfma_f32_32x32x16_bf16 v[96:111], v[192:195], v[128:131], v[96:111]
	s_waitcnt lgkmcnt(2)
	v_mfma_f32_32x32x16_bf16 v[80:95], v[196:199], v[128:131], v[80:95]
	v_add_u32_e32 v200, v0, v162
	ds_read_b128 v[192:195], v200
	ds_read_b128 v[196:199], v200 offset:8192
	s_waitcnt lgkmcnt(3)
	v_mfma_f32_32x32x16_bf16 v[96:111], v[2:5], v[132:135], v[96:111]
	s_waitcnt lgkmcnt(2)
	v_mfma_f32_32x32x16_bf16 v[80:95], v[6:9], v[132:135], v[80:95]
	v_add_u32_e32 v201, v0, v163
	ds_read_b128 v[2:5], v201
	ds_read_b128 v[6:9], v201 offset:8192
	s_waitcnt lgkmcnt(3)
	v_mfma_f32_32x32x16_bf16 v[96:111], v[192:195], v[136:139], v[96:111]
	s_waitcnt lgkmcnt(2)
	v_mfma_f32_32x32x16_bf16 v[80:95], v[196:199], v[136:139], v[80:95]
	s_waitcnt lgkmcnt(1)
	v_mfma_f32_32x32x16_bf16 v[96:111], v[2:5], v[140:143], v[96:111]
	s_waitcnt lgkmcnt(0)
	v_mfma_f32_32x32x16_bf16 v[80:95], v[6:9], v[140:143], v[80:95]
	v_add_u32_e32 v201, s51, v164
	v_add_u32_e32 v202, s51, v165
	v_add_u32_e32 v203, s51, v166
	v_add_u32_e32 v204, s51, v167
	ds_read_b64_tr_b16 v[192:193], v201 offset:16384
	ds_read_b64_tr_b16 v[194:195], v202 offset:2048
	ds_read_b64_tr_b16 v[196:197], v203 offset:16384
	ds_read_b64_tr_b16 v[198:199], v204 offset:2048
	v_add_u32_e32 v2, s51, v168
	v_add_u32_e32 v3, s51, v169
	v_add_u32_e32 v4, s51, v170
	v_add_u32_e32 v5, s51, v171
	ds_read_b64_tr_b16 v[226:227], v2 offset:16384
	ds_read_b64_tr_b16 v[228:229], v3 offset:2048
	v_max_f32_e32 v15, v96, v80
	v_max3_f32 v15, v15, v97, v81
	v_max3_f32 v15, v15, v98, v82
	v_max3_f32 v15, v15, v99, v83
	v_max3_f32 v15, v15, v100, v84
	v_max3_f32 v15, v15, v101, v85
	v_max3_f32 v15, v15, v102, v86
	v_max3_f32 v15, v15, v103, v87
	v_max3_f32 v15, v15, v104, v88
	v_max3_f32 v15, v15, v105, v89
	v_max3_f32 v15, v15, v106, v90
	v_max3_f32 v15, v15, v107, v91
	v_max3_f32 v15, v15, v108, v92
	v_max3_f32 v15, v15, v109, v93
	v_max3_f32 v15, v15, v110, v94
	v_max3_f32 v15, v15, v111, v95
	v_mul_f32_e64 v15, v15, s20
	ds_bpermute_b32 v14, v14, v15
	s_waitcnt lgkmcnt(0)
	v_max3_f32 v0, v175, v15, v14
	v_sub_f32_e32 v14, v175, v0
	v_exp_f32_e32 v14, v14
	s_nop 0
	v_cmp_neq_f32_e32 vcc, 1.0, v14
	s_cbranch_vccz .LBB0_466
	v_pk_mul_f32 v[78:79], v[78:79], v[14:15] op_sel_hi:[1,0]
	v_pk_mul_f32 v[76:77], v[76:77], v[14:15] op_sel_hi:[1,0]
	v_pk_mul_f32 v[74:75], v[74:75], v[14:15] op_sel_hi:[1,0]
	v_pk_mul_f32 v[72:73], v[72:73], v[14:15] op_sel_hi:[1,0]
	v_pk_mul_f32 v[70:71], v[70:71], v[14:15] op_sel_hi:[1,0]
	v_pk_mul_f32 v[68:69], v[68:69], v[14:15] op_sel_hi:[1,0]
	v_pk_mul_f32 v[66:67], v[66:67], v[14:15] op_sel_hi:[1,0]
	v_pk_mul_f32 v[64:65], v[64:65], v[14:15] op_sel_hi:[1,0]
	v_pk_mul_f32 v[62:63], v[62:63], v[14:15] op_sel_hi:[1,0]
	v_pk_mul_f32 v[60:61], v[60:61], v[14:15] op_sel_hi:[1,0]
	v_pk_mul_f32 v[58:59], v[58:59], v[14:15] op_sel_hi:[1,0]
	v_pk_mul_f32 v[56:57], v[56:57], v[14:15] op_sel_hi:[1,0]
	v_pk_mul_f32 v[54:55], v[54:55], v[14:15] op_sel_hi:[1,0]
	v_pk_mul_f32 v[52:53], v[52:53], v[14:15] op_sel_hi:[1,0]
	v_pk_mul_f32 v[50:51], v[50:51], v[14:15] op_sel_hi:[1,0]
	v_pk_mul_f32 v[48:49], v[48:49], v[14:15] op_sel_hi:[1,0]
	v_pk_mul_f32 v[46:47], v[46:47], v[14:15] op_sel_hi:[1,0]
	v_pk_mul_f32 v[44:45], v[44:45], v[14:15] op_sel_hi:[1,0]
	v_pk_mul_f32 v[42:43], v[42:43], v[14:15] op_sel_hi:[1,0]
	v_pk_mul_f32 v[40:41], v[40:41], v[14:15] op_sel_hi:[1,0]
	v_pk_mul_f32 v[38:39], v[38:39], v[14:15] op_sel_hi:[1,0]
	v_pk_mul_f32 v[36:37], v[36:37], v[14:15] op_sel_hi:[1,0]
	v_pk_mul_f32 v[34:35], v[34:35], v[14:15] op_sel_hi:[1,0]
	v_pk_mul_f32 v[32:33], v[32:33], v[14:15] op_sel_hi:[1,0]
	v_pk_mul_f32 v[30:31], v[30:31], v[14:15] op_sel_hi:[1,0]
	v_pk_mul_f32 v[28:29], v[28:29], v[14:15] op_sel_hi:[1,0]
	v_pk_mul_f32 v[26:27], v[26:27], v[14:15] op_sel_hi:[1,0]
	v_pk_mul_f32 v[24:25], v[24:25], v[14:15] op_sel_hi:[1,0]
	v_pk_mul_f32 v[22:23], v[22:23], v[14:15] op_sel_hi:[1,0]
	v_pk_mul_f32 v[20:21], v[20:21], v[14:15] op_sel_hi:[1,0]
	v_pk_mul_f32 v[18:19], v[18:19], v[14:15] op_sel_hi:[1,0]
	v_pk_mul_f32 v[16:17], v[16:17], v[14:15] op_sel_hi:[1,0]
; #define LAS __attribute__((address_space(3)))
; __device__ __forceinline__ unsigned pk2(float lo, float hi) { f32x2 v = {lo, hi}; bf16x2_t b = __builtin_convertvector(v, bf16x2_t); return __builtin_bit_cast(unsigned, b); }
; #define MFMA32(a, b, c) __builtin_amdgcn_mfma_f32_32x32x16_bf16((a), (b), (c), 0, 0, 0)
; template <int KSTEPS, class Pol>
; __device__ __forceinline__ void attn_pass(LAS unsigned char* lds, const Pol& P, const bf16_t* qb, int ldq, const bf16_t* kb, int ldk, const bf16_t* vb, int ldv,
;                                           float qs, f32x16 (&O)[4], float& m, float& l) {
;     ...
;             const f32x2 nm = {-mnew, -mnew};
; #pragma unroll
;             for (int i = 0; i < 16; i += 2) { const f32x2 a = (f32x2){S0[i], S0[i + 1]} + nm, b = (f32x2){S1[i], S1[i + 1]} + nm; S0[i] = a.x; S0[i + 1] = a.y; S1[i] = b.x; S1[i + 1] = b.y; }
;         }
;         f32x2 ls2 = {0.f, 0.f};
; #pragma unroll
;         for (int s = 0; s < 4; ++s) {
;             unsigned w[4];
; #pragma unroll
;             for (int e = 0; e < 4; ++e) {
;                 const int i = 8 * (s & 1) + 2 * e;
;                 f32x2 pv;
;                 pv.x = __builtin_amdgcn_exp2f(s < 2 ? S0[i] : S1[i]); pv.y = __builtin_amdgcn_exp2f(s < 2 ? S0[i + 1] : S1[i + 1]);
;                 ls2 = ls2 + pv;
;                 w[e] = pk2(pv.x, pv.y);
;             }
;             u32x4 wv; wv.x = w[0]; wv.y = w[1]; wv.z = w[2]; wv.w = w[3];
;             pf[s] = __builtin_bit_cast(bf16x8, wv);
;         }
;         l = l * alpha + (ls2.x + ls2.y);
;     ...
;     auto pv_acc = [&](int st) __attribute__((always_inline)) {
;         LAS unsigned char* Vb = lds + st * A_STAGE;
; #pragma unroll
;         for (int s = 0; s < 4; ++s) {
; #pragma unroll
;             for (int blk = 0; blk < 4; ++blk) {
;                 const s16x4 lo = __builtin_amdgcn_ds_read_tr16_b64_v4i16((LAS s16x4*)(Vb + s * 4096 + voffs[blk][0]));
;                 const s16x4 hi = __builtin_amdgcn_ds_read_tr16_b64_v4i16((LAS s16x4*)(Vb + s * 4096 + voffs[blk][1]));
;                 const bf16x8 va = __builtin_shufflevector(lo, hi, 0, 1, 2, 3, 4, 5, 6, 7);
;                 O[blk] = MFMA32(va, pf[s], O[blk]);
;             }
;         }
.LBB0_466:
	v_pk_fma_f32 v[96:97], v[96:97], s[20:21], v[0:1] op_sel_hi:[1,0,0] neg_lo:[0,0,1] neg_hi:[0,0,1]
	v_pk_fma_f32 v[98:99], v[98:99], s[20:21], v[0:1] op_sel_hi:[1,0,0] neg_lo:[0,0,1] neg_hi:[0,0,1]
	v_pk_fma_f32 v[100:101], v[100:101], s[20:21], v[0:1] op_sel_hi:[1,0,0] neg_lo:[0,0,1] neg_hi:[0,0,1]
	v_pk_fma_f32 v[102:103], v[102:103], s[20:21], v[0:1] op_sel_hi:[1,0,0] neg_lo:[0,0,1] neg_hi:[0,0,1]
	v_exp_f32_e32 v96, v96
	v_exp_f32_e32 v97, v97
	v_exp_f32_e32 v98, v98
	v_exp_f32_e32 v99, v99
	v_exp_f32_e32 v100, v100
	v_exp_f32_e32 v101, v101
	v_exp_f32_e32 v102, v102
	v_exp_f32_e32 v103, v103
	v_pk_fma_f32 v[104:105], v[104:105], s[20:21], v[0:1] op_sel_hi:[1,0,0] neg_lo:[0,0,1] neg_hi:[0,0,1]
	v_pk_fma_f32 v[106:107], v[106:107], s[20:21], v[0:1] op_sel_hi:[1,0,0] neg_lo:[0,0,1] neg_hi:[0,0,1]
	v_cvt_pk_bf16_f32 v6, v96, v97
	v_cvt_pk_bf16_f32 v7, v98, v99
	v_cvt_pk_bf16_f32 v8, v100, v101
	v_cvt_pk_bf16_f32 v9, v102, v103
	v_pk_fma_f32 v[108:109], v[108:109], s[20:21], v[0:1] op_sel_hi:[1,0,0] neg_lo:[0,0,1] neg_hi:[0,0,1]
	v_pk_fma_f32 v[110:111], v[110:111], s[20:21], v[0:1] op_sel_hi:[1,0,0] neg_lo:[0,0,1] neg_hi:[0,0,1]
	v_pk_add_f32 v[224:225], v[96:97], v[98:99]
	s_waitcnt lgkmcnt(4)
	v_mfma_f32_32x32x16_bf16 v[64:79], v[192:195], v[6:9], v[64:79]
	ds_read_b64_tr_b16 v[192:193], v4 offset:16384
	ds_read_b64_tr_b16 v[194:195], v5 offset:2048
	v_exp_f32_e32 v104, v104
	v_exp_f32_e32 v105, v105
	v_exp_f32_e32 v106, v106
	v_exp_f32_e32 v107, v107
	v_pk_add_f32 v[224:225], v[100:101], v[224:225]
	s_waitcnt lgkmcnt(4)
	v_mfma_f32_32x32x16_bf16 v[48:63], v[196:199], v[6:9], v[48:63]
	ds_read_b64_tr_b16 v[196:197], v201 offset:20480
	ds_read_b64_tr_b16 v[198:199], v202 offset:6144
	v_exp_f32_e32 v108, v108
	v_exp_f32_e32 v109, v109
	v_exp_f32_e32 v110, v110
	v_exp_f32_e32 v111, v111
	v_pk_add_f32 v[224:225], v[102:103], v[224:225]
	s_waitcnt lgkmcnt(4)
	v_mfma_f32_32x32x16_bf16 v[32:47], v[226:229], v[6:9], v[32:47]
	ds_read_b64_tr_b16 v[226:227], v203 offset:20480
	ds_read_b64_tr_b16 v[228:229], v204 offset:6144
	v_cvt_pk_bf16_f32 v10, v104, v105
	v_cvt_pk_bf16_f32 v11, v106, v107
	v_cvt_pk_bf16_f32 v12, v108, v109
	v_cvt_pk_bf16_f32 v13, v110, v111
	v_pk_add_f32 v[224:225], v[104:105], v[224:225]
	s_waitcnt lgkmcnt(4)
	v_mfma_f32_32x32x16_bf16 v[16:31], v[192:195], v[6:9], v[16:31]
	ds_read_b64_tr_b16 v[192:193], v2 offset:20480
	ds_read_b64_tr_b16 v[194:195], v3 offset:6144
	v_pk_add_f32 v[224:225], v[106:107], v[224:225]
	v_pk_fma_f32 v[80:81], v[80:81], s[20:21], v[0:1] op_sel_hi:[1,0,0] neg_lo:[0,0,1] neg_hi:[0,0,1]
	v_pk_fma_f32 v[82:83], v[82:83], s[20:21], v[0:1] op_sel_hi:[1,0,0] neg_lo:[0,0,1] neg_hi:[0,0,1]
	v_pk_fma_f32 v[84:85], v[84:85], s[20:21], v[0:1] op_sel_hi:[1,0,0] neg_lo:[0,0,1] neg_hi:[0,0,1]
	v_pk_fma_f32 v[86:87], v[86:87], s[20:21], v[0:1] op_sel_hi:[1,0,0] neg_lo:[0,0,1] neg_hi:[0,0,1]
	s_waitcnt lgkmcnt(4)
	v_mfma_f32_32x32x16_bf16 v[64:79], v[196:199], v[10:13], v[64:79]
	ds_read_b64_tr_b16 v[196:197], v4 offset:20480
	ds_read_b64_tr_b16 v[198:199], v5 offset:6144
	v_exp_f32_e32 v80, v80
	v_exp_f32_e32 v81, v81
	v_exp_f32_e32 v82, v82
	v_exp_f32_e32 v83, v83
	v_pk_add_f32 v[224:225], v[108:109], v[224:225]
	s_waitcnt lgkmcnt(4)
	v_mfma_f32_32x32x16_bf16 v[48:63], v[226:229], v[10:13], v[48:63]
	ds_read_b64_tr_b16 v[226:227], v201 offset:24576
	ds_read_b64_tr_b16 v[228:229], v202 offset:10240
	v_exp_f32_e32 v84, v84
	v_exp_f32_e32 v85, v85
	v_exp_f32_e32 v86, v86
	v_exp_f32_e32 v87, v87
	v_pk_add_f32 v[224:225], v[110:111], v[224:225]
	s_waitcnt lgkmcnt(4)
	v_mfma_f32_32x32x16_bf16 v[32:47], v[192:195], v[10:13], v[32:47]
	ds_read_b64_tr_b16 v[192:193], v203 offset:24576
	ds_read_b64_tr_b16 v[194:195], v204 offset:10240
	v_cvt_pk_bf16_f32 v6, v80, v81
	v_cvt_pk_bf16_f32 v7, v82, v83
	v_cvt_pk_bf16_f32 v8, v84, v85
	v_cvt_pk_bf16_f32 v9, v86, v87
	v_pk_add_f32 v[224:225], v[80:81], v[224:225]
	s_waitcnt lgkmcnt(4)
	v_mfma_f32_32x32x16_bf16 v[16:31], v[196:199], v[10:13], v[16:31]
	ds_read_b64_tr_b16 v[196:197], v2 offset:24576
	ds_read_b64_tr_b16 v[198:199], v3 offset:10240
	v_pk_add_f32 v[224:225], v[82:83], v[224:225]
	v_pk_fma_f32 v[88:89], v[88:89], s[20:21], v[0:1] op_sel_hi:[1,0,0] neg_lo:[0,0,1] neg_hi:[0,0,1]
	v_pk_fma_f32 v[90:91], v[90:91], s[20:21], v[0:1] op_sel_hi:[1,0,0] neg_lo:[0,0,1] neg_hi:[0,0,1]
	v_pk_fma_f32 v[92:93], v[92:93], s[20:21], v[0:1] op_sel_hi:[1,0,0] neg_lo:[0,0,1] neg_hi:[0,0,1]
	v_pk_fma_f32 v[94:95], v[94:95], s[20:21], v[0:1] op_sel_hi:[1,0,0] neg_lo:[0,0,1] neg_hi:[0,0,1]
	s_waitcnt lgkmcnt(4)
	v_mfma_f32_32x32x16_bf16 v[64:79], v[226:229], v[6:9], v[64:79]
	ds_read_b64_tr_b16 v[226:227], v4 offset:24576
	ds_read_b64_tr_b16 v[228:229], v5 offset:10240
	v_exp_f32_e32 v88, v88
	v_exp_f32_e32 v89, v89
	v_exp_f32_e32 v90, v90
	v_exp_f32_e32 v91, v91
	v_pk_add_f32 v[224:225], v[84:85], v[224:225]
	s_waitcnt lgkmcnt(4)
	v_mfma_f32_32x32x16_bf16 v[48:63], v[192:195], v[6:9], v[48:63]
	ds_read_b64_tr_b16 v[192:193], v201 offset:28672
	ds_read_b64_tr_b16 v[194:195], v202 offset:14336
	v_exp_f32_e32 v92, v92
	v_exp_f32_e32 v93, v93
	v_exp_f32_e32 v94, v94
	v_exp_f32_e32 v95, v95
	v_pk_add_f32 v[224:225], v[86:87], v[224:225]
	s_waitcnt lgkmcnt(4)
	v_mfma_f32_32x32x16_bf16 v[32:47], v[196:199], v[6:9], v[32:47]
	ds_read_b64_tr_b16 v[196:197], v203 offset:28672
	ds_read_b64_tr_b16 v[198:199], v204 offset:14336
	v_cvt_pk_bf16_f32 v10, v88, v89
	v_cvt_pk_bf16_f32 v11, v90, v91
	v_cvt_pk_bf16_f32 v12, v92, v93
	v_cvt_pk_bf16_f32 v13, v94, v95
	v_pk_add_f32 v[224:225], v[88:89], v[224:225]
	s_waitcnt lgkmcnt(4)
	v_mfma_f32_32x32x16_bf16 v[16:31], v[226:229], v[6:9], v[16:31]
	ds_read_b64_tr_b16 v[226:227], v2 offset:28672
	ds_read_b64_tr_b16 v[228:229], v3 offset:14336
	v_pk_add_f32 v[224:225], v[90:91], v[224:225]
	s_waitcnt lgkmcnt(4)
	v_mfma_f32_32x32x16_bf16 v[64:79], v[192:195], v[10:13], v[64:79]
	ds_read_b64_tr_b16 v[192:193], v4 offset:28672
	ds_read_b64_tr_b16 v[194:195], v5 offset:14336
	v_pk_add_f32 v[224:225], v[92:93], v[224:225]
	s_waitcnt lgkmcnt(4)
	v_mfma_f32_32x32x16_bf16 v[48:63], v[196:199], v[10:13], v[48:63]
	v_pk_add_f32 v[224:225], v[94:95], v[224:225]
	s_waitcnt lgkmcnt(2)
	v_mfma_f32_32x32x16_bf16 v[32:47], v[226:229], v[10:13], v[32:47]
	v_add_f32_e32 v15, v224, v225
	s_waitcnt lgkmcnt(0)
	v_mfma_f32_32x32x16_bf16 v[16:31], v[192:195], v[10:13], v[16:31]
	v_fmac_f32_e32 v15, v174, v14
	s_nop 0
	v_mov_b32_e32 v174, v15
	s_cmp_ge_i32 s49, s45
	s_cbranch_scc0 .LBB0_468
	s_branch .LBB0_473
